# fast-path Y block: removed 7 register copies left by the exp folding
# speedup vs baseline: 1.0753x; 1.0034x over previous
.Lf_459:
	v_mov_b32_e32 v180, v128
	v_mov_b32_e32 v181, v129
	v_mov_b32_e32 v182, v130
	v_mov_b32_e32 v183, v131
	v_mfma_f32_32x32x16_bf16 v[64:79], v[176:179], v[140:143], v[64:79]
	ds_read_b64_tr_b16 v[128:129], v0 offset:24576
	ds_read_b64_tr_b16 v[130:131], v0 offset:25088
	v_exp_f32_e32 v14, v112
	s_mov_b32 s61, s60
	s_mov_b32 s62, s60
	s_mov_b32 s63, s60
	v_mfma_f32_32x32x16_bf16 v[64:79], v[172:175], v[136:139], v[64:79]
	ds_read_b64_tr_b16 v[172:173], v0 offset:25600
	ds_read_b64_tr_b16 v[174:175], v0 offset:26112
	v_exp_f32_e32 v15, v96
	v_mfma_f32_32x32x16_bf16 v[64:79], v[168:171], v[132:135], v[64:79]
	ds_read_b64_tr_b16 v[168:169], v0 offset:26624
	ds_read_b64_tr_b16 v[170:171], v0 offset:27136
	v_exp_f32_e32 v96, v113
	v_mfma_f32_32x32x16_bf16 v[64:79], v[164:167], v[180:183], v[64:79]
	ds_read_b64_tr_b16 v[164:165], v0 offset:27648
	ds_read_b64_tr_b16 v[166:167], v0 offset:28160
	v_exp_f32_e32 v97, v97
	v_mfma_f32_32x32x16_bf16 v[48:63], v[160:163], v[140:143], v[48:63]
	ds_read_b64_tr_b16 v[160:161], v0 offset:28672
	ds_read_b64_tr_b16 v[162:163], v0 offset:29184
	v_exp_f32_e32 v112, v114
	v_mfma_f32_32x32x16_bf16 v[48:63], v[10:13], v[136:139], v[48:63]
	ds_read_b64_tr_b16 v[10:11], v0 offset:29696
	ds_read_b64_tr_b16 v[12:13], v0 offset:30208
	v_exp_f32_e32 v98, v98
	v_mfma_f32_32x32x16_bf16 v[48:63], v[6:9], v[132:135], v[48:63]
	ds_read_b64_tr_b16 v[6:7], v0 offset:30720
	ds_read_b64_tr_b16 v[8:9], v0 offset:31232
	v_exp_f32_e32 v113, v115
	v_mfma_f32_32x32x16_bf16 v[48:63], v[2:5], v[180:183], v[48:63]
	ds_read_b64_tr_b16 v[2:3], v0 offset:31744
	ds_read_b64_tr_b16 v[4:5], v0 offset:32256
	v_exp_f32_e32 v0, v99
	s_waitcnt lgkmcnt(14)
	v_mfma_f32_32x32x16_bf16 v[32:47], v[128:131], v[140:143], v[32:47]
	v_exp_f32_e32 v99, v116
	v_exp_f32_e32 v100, v100
	v_exp_f32_e32 v114, v117
	s_waitcnt lgkmcnt(12)
	v_mfma_f32_32x32x16_bf16 v[32:47], v[172:175], v[136:139], v[32:47]
	v_exp_f32_e32 v101, v101
	v_exp_f32_e32 v115, v118
	v_exp_f32_e32 v102, v102
	s_waitcnt lgkmcnt(10)
	v_mfma_f32_32x32x16_bf16 v[32:47], v[168:171], v[132:135], v[32:47]
	v_exp_f32_e32 v116, v119
	v_exp_f32_e32 v103, v103
	v_exp_f32_e32 v117, v120
	s_waitcnt lgkmcnt(8)
	v_mfma_f32_32x32x16_bf16 v[32:47], v[164:167], v[180:183], v[32:47]
	v_exp_f32_e32 v104, v104
	v_exp_f32_e32 v118, v121
	v_exp_f32_e32 v105, v105
	s_waitcnt lgkmcnt(6)
	v_mfma_f32_32x32x16_bf16 v[16:31], v[160:163], v[140:143], v[16:31]
	v_exp_f32_e32 v119, v122
	v_exp_f32_e32 v106, v106
	v_exp_f32_e32 v120, v123
	s_waitcnt lgkmcnt(4)
	v_mfma_f32_32x32x16_bf16 v[16:31], v[10:13], v[136:139], v[16:31]
	v_exp_f32_e32 v10, v107
	v_exp_f32_e32 v11, v124
	v_exp_f32_e32 v12, v108
	s_waitcnt lgkmcnt(2)
	v_mfma_f32_32x32x16_bf16 v[16:31], v[6:9], v[132:135], v[16:31]
	v_exp_f32_e32 v6, v125
	v_exp_f32_e32 v7, v109
	v_exp_f32_e32 v8, v126
	s_waitcnt lgkmcnt(0)
	v_mfma_f32_32x32x16_bf16 v[16:31], v[2:5], v[180:183], v[16:31]
	v_mov_b64_e32 v[2:3], s[60:61]
	v_mov_b64_e32 v[4:5], s[62:63]
	v_exp_f32_e32 v107, v110
	v_mfma_f32_32x32x16_bf16 v[80:95], v[2:5], v[140:143], v[80:95]
	v_exp_f32_e32 v108, v127
	v_exp_f32_e32 v109, v111
	v_cvt_pk_bf16_f32 v140, v14, v96
	v_cvt_pk_bf16_f32 v143, v115, v116
	v_mfma_f32_32x32x16_bf16 v[80:95], v[2:5], v[136:139], v[80:95]
	v_cvt_pk_bf16_f32 v128, v104, v105
	v_cvt_pk_bf16_f32 v141, v112, v113
	v_cvt_pk_bf16_f32 v136, v117, v118
	v_mfma_f32_32x32x16_bf16 v[80:95], v[2:5], v[132:135], v[80:95]
	v_cvt_pk_bf16_f32 v137, v119, v120
	v_cvt_pk_bf16_f32 v129, v106, v10
	v_cvt_pk_bf16_f32 v132, v15, v97
	v_cvt_pk_bf16_f32 v130, v12, v7
	v_cvt_pk_bf16_f32 v138, v11, v6
	v_cvt_pk_bf16_f32 v133, v98, v0
	v_cvt_pk_bf16_f32 v142, v99, v114
	v_cvt_pk_bf16_f32 v134, v100, v101
	v_cvt_pk_bf16_f32 v135, v102, v103
	v_cvt_pk_bf16_f32 v139, v8, v108
	v_cvt_pk_bf16_f32 v131, v107, v109
	v_mfma_f32_32x32x16_bf16 v[80:95], v[2:5], v[180:183], v[80:95]
	s_add_i32 s28, s28, 1
	s_add_i32 s13, s13, 1
	s_add_i32 s19, s19, 0x8000
	s_cmpk_eq_i32 s13, 0x45
	s_cbranch_scc1 .LBB0_464
